# GEMM phase pre-loop: column-constant (ctab) loads batched, one wait instead of up to 6 serialized round trips (up + in phases), on v21
# speedup vs baseline: 1.0033x; 1.0033x over previous
.LBB0_563:
	s_and_b64 vcc, exec, s[0:1]
	s_cbranch_vccz .LBB0_763
	v_readlane_b32 s0, v255, 3
	v_readlane_b32 s1, v255, 4
	s_add_u32 s14, s0, 0x16000
	s_addc_u32 s15, s1, 0
	s_add_u32 s16, s0, 0x1b800
	s_addc_u32 s17, s1, 0
	s_cmpk_lt_i32 s55, 0x2c0
	v_mbcnt_lo_u32_b32 v1, -1, 0
	v_mbcnt_hi_u32_b32 v1, -1, v1
	s_cselect_b64 s[0:1], -1, 0
	s_cmpk_gt_i32 s55, 0x2bf
	s_waitcnt vmcnt(0) lgkmcnt(0)
	v_add_u32_e32 v4, s86, v1
	s_cbranch_scc1 .LBB0_568
	s_movk_i32 s3, 0x100
	v_cmp_gt_i32_e32 vcc, s3, v4
	s_ashr_i32 s3, s55, 31
	s_lshr_b32 s3, s3, 29
	s_add_i32 s3, s55, s3
	s_ashr_i32 s6, s3, 3
	s_and_b32 s3, s3, -8
	s_sub_i32 s3, s55, s3
	s_cmp_lt_i32 s3, 0
	s_movk_i32 s7, 0x59
	s_cselect_b32 s7, s7, 0x58
	s_mul_i32 s3, s7, s3
	s_add_i32 s3, s3, s6
	s_mul_hi_i32 s6, s3, 0x2e8ba2e9
	s_lshr_b32 s7, s6, 31
	s_lshr_b32 s6, s6, 3
	s_add_i32 s6, s6, s7
	s_mul_i32 s6, s6, 44
	s_sub_i32 s3, s3, s6
	s_bfe_i32 s6, s3, 0x80000
	s_bfe_u32 s6, s6, 0x2000d
	s_add_i32 s3, s3, s6
	v_mov_b32_e32 v2, s17
	v_mov_b32_e32 v3, s15
	s_bfe_i32 s3, s3, 0x80000
	v_cndmask_b32_e32 v3, v2, v3, vcc
	v_mov_b32_e32 v2, s16
	v_mov_b32_e32 v5, s14
	s_sext_i32_i16 s3, s3
	v_cndmask_b32_e32 v2, v2, v5, vcc
	v_and_b32_e32 v5, 0xff, v4
	s_ashr_i32 s3, s3, 2
	v_lshl_or_b32 v6, s3, 8, v5
	v_ashrrev_i32_e32 v7, 31, v6
	v_lshl_add_u64 v[6:7], v[6:7], 3, v[2:3]
	global_load_dwordx2 v[12:13], v[6:7], off
	v_lshl_add_u32 v6, v4, 2, 0
	v_add_u32_e32 v6, 0x20400, v6
	s_cmpk_gt_i32 s55, 0x1bf
	s_cbranch_scc1 .Lctab_in_b
	s_add_i32 s3, s55, 0x100
	s_ashr_i32 s6, s3, 31
	s_lshr_b32 s6, s6, 29
	s_add_i32 s6, s3, s6
	s_ashr_i32 s7, s6, 3
	s_and_b32 s6, s6, -8
	s_sub_i32 s3, s3, s6
	s_cmp_lt_i32 s3, 0
	s_movk_i32 s6, 0x59
	s_cselect_b32 s6, s6, 0x58
	s_mul_i32 s3, s6, s3
	s_add_i32 s3, s3, s7
	s_mul_hi_i32 s6, s3, 0x2e8ba2e9
	s_lshr_b32 s7, s6, 31
	s_lshr_b32 s6, s6, 3
	s_add_i32 s6, s6, s7
	s_mul_i32 s6, s6, 44
	s_sub_i32 s3, s3, s6
	s_bfe_i32 s6, s3, 0x80000
	s_bfe_u32 s6, s6, 0x2000d
	s_add_i32 s3, s3, s6
	s_bfe_i32 s3, s3, 0x80000
	s_sext_i32_i16 s3, s3
	s_ashr_i32 s3, s3, 2
	v_lshl_or_b32 v8, s3, 8, v5
	v_ashrrev_i32_e32 v9, 31, v8
	v_lshl_add_u64 v[8:9], v[8:9], 3, v[2:3]
	global_load_dwordx2 v[14:15], v[8:9], off
	s_cmpk_gt_i32 s55, 0xbf
	s_cbranch_scc1 .Lctab_in_b
	s_add_i32 s3, s55, 0x200
	s_ashr_i32 s6, s3, 31
	s_lshr_b32 s6, s6, 29
	s_add_i32 s6, s3, s6
	s_ashr_i32 s7, s6, 3
	s_and_b32 s6, s6, -8
	s_sub_i32 s3, s3, s6
	s_cmp_lt_i32 s3, 0
	s_movk_i32 s6, 0x59
	s_cselect_b32 s6, s6, 0x58
	s_mul_i32 s3, s6, s3
	s_add_i32 s3, s3, s7
	s_mul_hi_i32 s6, s3, 0x2e8ba2e9
	s_lshr_b32 s7, s6, 31
	s_lshr_b32 s6, s6, 3
	s_add_i32 s6, s6, s7
	s_mul_i32 s6, s6, 44
	s_sub_i32 s3, s3, s6
	s_bfe_i32 s6, s3, 0x80000
	s_bfe_u32 s6, s6, 0x2000d
	s_add_i32 s3, s3, s6
	s_bfe_i32 s3, s3, 0x80000
	s_sext_i32_i16 s3, s3
	s_ashr_i32 s3, s3, 2
	v_lshl_or_b32 v8, s3, 8, v5
	v_ashrrev_i32_e32 v9, 31, v8
	v_lshl_add_u64 v[2:3], v[8:9], 3, v[2:3]
	global_load_dwordx2 v[16:17], v[2:3], off
.Lctab_in_b:
	s_waitcnt vmcnt(0) lgkmcnt(0)
	v_cvt_f64_i32_e32 v[10:11], v13
	v_cvt_f64_u32_e32 v[8:9], v12
	v_ldexp_f64 v[10:11], v[10:11], 32
	v_add_f64 v[8:9], v[10:11], v[8:9]
	v_ldexp_f64 v[8:9], v[8:9], s2
	v_cvt_f32_f64_e32 v7, v[8:9]
	ds_write_b32 v6, v7
	s_cmpk_gt_i32 s55, 0x1bf
	s_cbranch_scc1 .LBB0_568
	v_cvt_f64_i32_e32 v[10:11], v15
	v_cvt_f64_u32_e32 v[8:9], v14
	v_ldexp_f64 v[10:11], v[10:11], 32
	v_add_f64 v[8:9], v[10:11], v[8:9]
	v_ldexp_f64 v[8:9], v[8:9], s2
	v_cvt_f32_f64_e32 v7, v[8:9]
	ds_write_b32 v6, v7 offset:2048
	s_cmpk_gt_i32 s55, 0xbf
	s_cbranch_scc1 .LBB0_568
	v_cvt_f64_i32_e32 v[10:11], v17
	v_cvt_f64_u32_e32 v[8:9], v16
	v_ldexp_f64 v[10:11], v[10:11], 32
	v_add_f64 v[8:9], v[10:11], v[8:9]
	v_ldexp_f64 v[8:9], v[8:9], s2
	v_cvt_f32_f64_e32 v7, v[8:9]
	ds_write_b32 v6, v7 offset:4096

.LBB0_928:
	s_and_b64 vcc, exec, s[0:1]
	s_movk_i32 s76, 0x3fe
	s_movk_i32 s77, 0x3fc
	s_movk_i32 s85, 0x3fa
	s_movk_i32 s84, 0x3f8
	s_movk_i32 s81, 0x3f6
	s_movk_i32 s88, 0x3f4
	s_movk_i32 s89, 0x3f2
	s_movk_i32 s24, 0x3f0
	s_movk_i32 s25, 0x3ee
	s_movk_i32 s26, 0x3ec
	s_movk_i32 s27, 0x3ea
	s_movk_i32 s28, 0x3e8
	s_movk_i32 s29, 0x3e6
	s_movk_i32 s30, 0x3e4
	s_movk_i32 s31, 0x3e2
	s_movk_i32 s36, 0x3de
	s_movk_i32 s37, 0x3dc
	s_movk_i32 s38, 0x3da
	s_movk_i32 s39, 0x3d8
	s_movk_i32 s40, 0x3d6
	s_movk_i32 s41, 0x3d4
	s_movk_i32 s42, 0x3d2
	s_movk_i32 s43, 0x3d0
	s_movk_i32 s44, 0x3ce
	s_movk_i32 s45, 0x3cc
	s_movk_i32 s46, 0x3ca
	s_movk_i32 s47, 0x3c8
	s_movk_i32 s48, 0x3c6
	s_movk_i32 s49, 0x3c4
	s_cbranch_vccz .LBB0_311
	s_cmp_lg_u32 s33, 0
	s_cselect_b64 s[6:7], -1, 0
	s_cmp_eq_u32 s33, 0
	s_cselect_b64 s[8:9], -1, 0
	s_and_b64 s[0:1], s[8:9], exec
	s_cselect_b32 s0, 0, 0x21000
	s_mov_b32 s1, 0xb000
	v_readlane_b32 s4, v255, 3
	s_cselect_b32 s1, s1, 0x2c000
	v_readlane_b32 s5, v255, 4
	s_add_u32 s10, s4, s0
	s_addc_u32 s11, s5, 0
	s_add_u32 s12, s4, s1
	s_addc_u32 s13, s5, 0
	s_cmpk_lt_i32 s55, 0x580
	v_mbcnt_lo_u32_b32 v1, -1, 0
	v_mbcnt_hi_u32_b32 v1, -1, v1
	s_cselect_b64 s[0:1], -1, 0
	s_cmpk_gt_i32 s55, 0x57f
	s_waitcnt vmcnt(0) lgkmcnt(0)
	v_add_u32_e32 v4, s86, v1
	s_cbranch_scc1 .LBB0_936
	s_movk_i32 s3, 0x100
	v_cmp_gt_i32_e32 vcc, s3, v4
	s_ashr_i32 s3, s55, 31
	s_lshr_b32 s3, s3, 29
	s_add_i32 s3, s55, s3
	s_ashr_i32 s4, s3, 3
	s_and_b32 s3, s3, -8
	s_sub_i32 s3, s55, s3
	s_cmp_lt_i32 s3, 0
	s_movk_i32 s5, 0xb1
	s_cselect_b32 s5, s5, 0xb0
	s_mul_i32 s3, s5, s3
	s_add_i32 s3, s3, s4
	s_mul_hi_i32 s4, s3, 0x2e8ba2e9
	s_lshr_b32 s5, s4, 31
	s_lshr_b32 s4, s4, 4
	s_add_i32 s4, s4, s5
	s_mulk_i32 s4, 0x58
	s_sub_i32 s3, s3, s4
	s_bfe_i32 s4, s3, 0x80000
	s_bfe_u32 s4, s4, 0x2000d
	s_add_i32 s3, s3, s4
	v_mov_b32_e32 v2, s13
	v_mov_b32_e32 v3, s11
	s_bfe_i32 s3, s3, 0x80000
	v_cndmask_b32_e32 v3, v2, v3, vcc
	v_mov_b32_e32 v2, s12
	v_mov_b32_e32 v5, s10
	s_sext_i32_i16 s3, s3
	v_cndmask_b32_e32 v2, v2, v5, vcc
	v_and_b32_e32 v5, 0xff, v4
	s_ashr_i32 s3, s3, 2
	v_lshl_or_b32 v6, s3, 8, v5
	v_ashrrev_i32_e32 v7, 31, v6
	v_lshl_add_u64 v[6:7], v[6:7], 3, v[2:3]
	global_load_dwordx2 v[12:13], v[6:7], off
	v_lshl_add_u32 v6, v4, 2, 0
	v_add_u32_e32 v6, 0x20400, v6
	s_cmpk_gt_i32 s55, 0x47f
	s_cbranch_scc1 .Lctab_up_b
	s_add_i32 s3, s55, 0x100
	s_ashr_i32 s4, s3, 31
	s_lshr_b32 s4, s4, 29
	s_add_i32 s4, s3, s4
	s_ashr_i32 s5, s4, 3
	s_and_b32 s4, s4, -8
	s_sub_i32 s3, s3, s4
	s_cmp_lt_i32 s3, 0
	s_movk_i32 s4, 0xb1
	s_cselect_b32 s4, s4, 0xb0
	s_mul_i32 s3, s4, s3
	s_add_i32 s3, s3, s5
	s_mul_hi_i32 s4, s3, 0x2e8ba2e9
	s_lshr_b32 s5, s4, 31
	s_lshr_b32 s4, s4, 4
	s_add_i32 s4, s4, s5
	s_mulk_i32 s4, 0x58
	s_sub_i32 s3, s3, s4
	s_bfe_i32 s4, s3, 0x80000
	s_bfe_u32 s4, s4, 0x2000d
	s_add_i32 s3, s3, s4
	s_bfe_i32 s3, s3, 0x80000
	s_sext_i32_i16 s3, s3
	s_ashr_i32 s3, s3, 2
	v_lshl_or_b32 v8, s3, 8, v5
	v_ashrrev_i32_e32 v9, 31, v8
	v_lshl_add_u64 v[8:9], v[8:9], 3, v[2:3]
	global_load_dwordx2 v[14:15], v[8:9], off
	s_cmpk_gt_i32 s55, 0x37f
	s_cbranch_scc1 .Lctab_up_b
	s_add_i32 s3, s55, 0x200
	s_ashr_i32 s4, s3, 31
	s_lshr_b32 s4, s4, 29
	s_add_i32 s4, s3, s4
	s_ashr_i32 s5, s4, 3
	s_and_b32 s4, s4, -8
	s_sub_i32 s3, s3, s4
	s_cmp_lt_i32 s3, 0
	s_movk_i32 s4, 0xb1
	s_cselect_b32 s4, s4, 0xb0
	s_mul_i32 s3, s4, s3
	s_add_i32 s3, s3, s5
	s_mul_hi_i32 s4, s3, 0x2e8ba2e9
	s_lshr_b32 s5, s4, 31
	s_lshr_b32 s4, s4, 4
	s_add_i32 s4, s4, s5
	s_mulk_i32 s4, 0x58
	s_sub_i32 s3, s3, s4
	s_bfe_i32 s4, s3, 0x80000
	s_bfe_u32 s4, s4, 0x2000d
	s_add_i32 s3, s3, s4
	s_bfe_i32 s3, s3, 0x80000
	s_sext_i32_i16 s3, s3
	s_ashr_i32 s3, s3, 2
	v_lshl_or_b32 v8, s3, 8, v5
	v_ashrrev_i32_e32 v9, 31, v8
	v_lshl_add_u64 v[8:9], v[8:9], 3, v[2:3]
	global_load_dwordx2 v[16:17], v[8:9], off
	s_cmpk_gt_i32 s55, 0x27f
	s_cbranch_scc1 .Lctab_up_b
	s_add_i32 s3, s55, 0x300
	s_ashr_i32 s4, s3, 31
	s_lshr_b32 s4, s4, 29
	s_add_i32 s4, s3, s4
	s_ashr_i32 s5, s4, 3
	s_and_b32 s4, s4, -8
	s_sub_i32 s3, s3, s4
	s_cmp_lt_i32 s3, 0
	s_movk_i32 s4, 0xb1
	s_cselect_b32 s4, s4, 0xb0
	s_mul_i32 s3, s4, s3
	s_add_i32 s3, s3, s5
	s_mul_hi_i32 s4, s3, 0x2e8ba2e9
	s_lshr_b32 s5, s4, 31
	s_lshr_b32 s4, s4, 4
	s_add_i32 s4, s4, s5
	s_mulk_i32 s4, 0x58
	s_sub_i32 s3, s3, s4
	s_bfe_i32 s4, s3, 0x80000
	s_bfe_u32 s4, s4, 0x2000d
	s_add_i32 s3, s3, s4
	s_bfe_i32 s3, s3, 0x80000
	s_sext_i32_i16 s3, s3
	s_ashr_i32 s3, s3, 2
	v_lshl_or_b32 v8, s3, 8, v5
	v_ashrrev_i32_e32 v9, 31, v8
	v_lshl_add_u64 v[8:9], v[8:9], 3, v[2:3]
	global_load_dwordx2 v[18:19], v[8:9], off
	s_cmpk_gt_i32 s55, 0x17f
	s_cbranch_scc1 .Lctab_up_b
	s_add_i32 s3, s55, 0x400
	s_ashr_i32 s4, s3, 31
	s_lshr_b32 s4, s4, 29
	s_add_i32 s4, s3, s4
	s_ashr_i32 s5, s4, 3
	s_and_b32 s4, s4, -8
	s_sub_i32 s3, s3, s4
	s_cmp_lt_i32 s3, 0
	s_movk_i32 s4, 0xb1
	s_cselect_b32 s4, s4, 0xb0
	s_mul_i32 s3, s4, s3
	s_add_i32 s3, s3, s5
	s_mul_hi_i32 s4, s3, 0x2e8ba2e9
	s_lshr_b32 s5, s4, 31
	s_lshr_b32 s4, s4, 4
	s_add_i32 s4, s4, s5
	s_mulk_i32 s4, 0x58
	s_sub_i32 s3, s3, s4
	s_bfe_i32 s4, s3, 0x80000
	s_bfe_u32 s4, s4, 0x2000d
	s_add_i32 s3, s3, s4
	s_bfe_i32 s3, s3, 0x80000
	s_sext_i32_i16 s3, s3
	s_ashr_i32 s3, s3, 2
	v_lshl_or_b32 v8, s3, 8, v5
	v_ashrrev_i32_e32 v9, 31, v8
	v_lshl_add_u64 v[8:9], v[8:9], 3, v[2:3]
	global_load_dwordx2 v[20:21], v[8:9], off
	s_cmpk_gt_i32 s55, 0x7f
	s_cbranch_scc1 .Lctab_up_b
	s_add_i32 s3, s55, 0x500
	s_ashr_i32 s4, s3, 31
	s_lshr_b32 s4, s4, 29
	s_add_i32 s4, s3, s4
	s_ashr_i32 s5, s4, 3
	s_and_b32 s4, s4, -8
	s_sub_i32 s3, s3, s4
	s_cmp_lt_i32 s3, 0
	s_movk_i32 s4, 0xb1
	s_cselect_b32 s4, s4, 0xb0
	s_mul_i32 s3, s4, s3
	s_add_i32 s3, s3, s5
	s_mul_hi_i32 s4, s3, 0x2e8ba2e9
	s_lshr_b32 s5, s4, 31
	s_lshr_b32 s4, s4, 4
	s_add_i32 s4, s4, s5
	s_mulk_i32 s4, 0x58
	s_sub_i32 s3, s3, s4
	s_bfe_i32 s4, s3, 0x80000
	s_bfe_u32 s4, s4, 0x2000d
	s_add_i32 s3, s3, s4
	s_bfe_i32 s3, s3, 0x80000
	s_sext_i32_i16 s3, s3
	s_ashr_i32 s3, s3, 2
	v_lshl_or_b32 v8, s3, 8, v5
	v_ashrrev_i32_e32 v9, 31, v8
	v_lshl_add_u64 v[2:3], v[8:9], 3, v[2:3]
	global_load_dwordx2 v[22:23], v[2:3], off
.Lctab_up_b:
	s_waitcnt vmcnt(0) lgkmcnt(0)
	v_cvt_f64_i32_e32 v[10:11], v13
	v_cvt_f64_u32_e32 v[8:9], v12
	v_ldexp_f64 v[10:11], v[10:11], 32
	v_add_f64 v[8:9], v[10:11], v[8:9]
	v_ldexp_f64 v[8:9], v[8:9], s2
	v_cvt_f32_f64_e32 v7, v[8:9]
	ds_write_b32 v6, v7
	s_cmpk_gt_i32 s55, 0x47f
	s_cbranch_scc1 .LBB0_936
	v_cvt_f64_i32_e32 v[10:11], v15
	v_cvt_f64_u32_e32 v[8:9], v14
	v_ldexp_f64 v[10:11], v[10:11], 32
	v_add_f64 v[8:9], v[10:11], v[8:9]
	v_ldexp_f64 v[8:9], v[8:9], s2
	v_cvt_f32_f64_e32 v7, v[8:9]
	ds_write_b32 v6, v7 offset:2048
	s_cmpk_gt_i32 s55, 0x37f
	s_cbranch_scc1 .LBB0_936
	v_cvt_f64_i32_e32 v[10:11], v17
	v_cvt_f64_u32_e32 v[8:9], v16
	v_ldexp_f64 v[10:11], v[10:11], 32
	v_add_f64 v[8:9], v[10:11], v[8:9]
	v_ldexp_f64 v[8:9], v[8:9], s2
	v_cvt_f32_f64_e32 v7, v[8:9]
	ds_write_b32 v6, v7 offset:4096
	s_cmpk_gt_i32 s55, 0x27f
	s_cbranch_scc1 .LBB0_936
	v_cvt_f64_i32_e32 v[10:11], v19
	v_cvt_f64_u32_e32 v[8:9], v18
	v_ldexp_f64 v[10:11], v[10:11], 32
	v_add_f64 v[8:9], v[10:11], v[8:9]
	v_ldexp_f64 v[8:9], v[8:9], s2
	v_cvt_f32_f64_e32 v7, v[8:9]
	ds_write_b32 v6, v7 offset:6144
	s_cmpk_gt_i32 s55, 0x17f
	s_cbranch_scc1 .LBB0_936
	v_cvt_f64_i32_e32 v[10:11], v21
	v_cvt_f64_u32_e32 v[8:9], v20
	v_ldexp_f64 v[10:11], v[10:11], 32
	v_add_f64 v[8:9], v[10:11], v[8:9]
	v_ldexp_f64 v[8:9], v[8:9], s2
	v_cvt_f32_f64_e32 v7, v[8:9]
	ds_write_b32 v6, v7 offset:8192
	s_cmpk_gt_i32 s55, 0x7f
	s_cbranch_scc1 .LBB0_936
	v_cvt_f64_i32_e32 v[10:11], v23
	v_cvt_f64_u32_e32 v[8:9], v22
	v_ldexp_f64 v[10:11], v[10:11], 32
	v_add_f64 v[8:9], v[10:11], v[8:9]
	v_ldexp_f64 v[8:9], v[8:9], s2
	v_cvt_f32_f64_e32 v7, v[8:9]
	ds_write_b32 v6, v7 offset:10240
